# s_setprio 1 before the MFMA-opening barrier + no-op fillers stripped from MFMA blocks, on top of v45
# speedup vs baseline: 1.0181x; 1.0110x over previous
.LBB0_233:
	ds_read_b128 v[130:133], v213
	ds_read_b128 v[134:137], v214
	ds_read_b128 v[138:141], v215
	ds_read_b128 v[142:145], v216
	ds_read_b128 v[146:149], v217
	ds_read_b128 v[150:153], v218
	ds_read_b128 v[154:157], v219
	ds_read_b128 v[158:161], v220
	s_add_i32 s4, s33, 0xffffe080
	s_cmp_eq_u32 s58, 12
	s_cselect_b32 s61, s18, s4
	s_cselect_b32 s60, s19, s57
	s_add_i32 s59, s61, 0x80
	s_mov_b32 s4, s70
	s_mov_b32 m0, s38
	ds_read_b128 v[162:165], v221
	ds_read_b128 v[166:169], v221 offset:2048
	ds_read_b128 v[170:173], v222
	ds_read_b128 v[174:177], v222 offset:2048
	ds_read_b128 v[178:181], v221 offset:4096
	ds_read_b128 v[182:185], v221 offset:6144
	ds_read_b128 v[186:189], v222 offset:4096
	ds_read_b128 v[190:193], v222 offset:6144
	buffer_load_dwordx4 v207, s[4:7], s33 offen lds
	s_mov_b32 m0, s41
	s_nop 0
	buffer_load_dwordx4 v209, s[4:7], s33 offen lds
	s_waitcnt vmcnt(8)
	s_waitcnt lgkmcnt(0)
	s_setprio 1
	s_barrier
	v_mfma_f32_16x16x32_bf16 v[114:117], v[130:133], v[162:165], v[114:117]
	v_mfma_f32_16x16x32_bf16 v[110:113], v[138:141], v[162:165], v[110:113]
	v_mfma_f32_16x16x32_bf16 v[106:109], v[130:133], v[166:169], v[106:109]
	v_mfma_f32_16x16x32_bf16 v[102:105], v[138:141], v[166:169], v[102:105]
	v_mfma_f32_16x16x32_bf16 v[98:101], v[130:133], v[178:181], v[98:101]
	v_mfma_f32_16x16x32_bf16 v[94:97], v[138:141], v[178:181], v[94:97]
	v_mfma_f32_16x16x32_bf16 v[90:93], v[130:133], v[182:185], v[90:93]
	v_mfma_f32_16x16x32_bf16 v[86:89], v[138:141], v[182:185], v[86:89]
	v_mfma_f32_16x16x32_bf16 v[114:117], v[134:137], v[170:173], v[114:117]
	v_mfma_f32_16x16x32_bf16 v[110:113], v[142:145], v[170:173], v[110:113]
	v_mfma_f32_16x16x32_bf16 v[106:109], v[134:137], v[174:177], v[106:109]
	v_mfma_f32_16x16x32_bf16 v[102:105], v[142:145], v[174:177], v[102:105]
	v_mfma_f32_16x16x32_bf16 v[98:101], v[134:137], v[186:189], v[98:101]
	v_mfma_f32_16x16x32_bf16 v[94:97], v[142:145], v[186:189], v[94:97]
	v_mfma_f32_16x16x32_bf16 v[90:93], v[134:137], v[190:193], v[90:93]
	v_mfma_f32_16x16x32_bf16 v[86:89], v[142:145], v[190:193], v[86:89]
	v_mfma_f32_16x16x32_bf16 v[82:85], v[146:149], v[162:165], v[82:85]
	v_mfma_f32_16x16x32_bf16 v[74:77], v[154:157], v[162:165], v[74:77]
	v_mfma_f32_16x16x32_bf16 v[70:73], v[146:149], v[166:169], v[70:73]
	v_mfma_f32_16x16x32_bf16 v[66:69], v[154:157], v[166:169], v[66:69]
	v_mfma_f32_16x16x32_bf16 v[62:65], v[146:149], v[178:181], v[62:65]
	v_mfma_f32_16x16x32_bf16 v[58:61], v[154:157], v[178:181], v[58:61]
	v_mfma_f32_16x16x32_bf16 v[54:57], v[146:149], v[182:185], v[54:57]
	v_mfma_f32_16x16x32_bf16 v[50:53], v[154:157], v[182:185], v[50:53]
	v_mfma_f32_16x16x32_bf16 v[82:85], v[150:153], v[170:173], v[82:85]
	v_mfma_f32_16x16x32_bf16 v[74:77], v[158:161], v[170:173], v[74:77]
	v_mfma_f32_16x16x32_bf16 v[70:73], v[150:153], v[174:177], v[70:73]
	v_mfma_f32_16x16x32_bf16 v[66:69], v[158:161], v[174:177], v[66:69]
	v_mfma_f32_16x16x32_bf16 v[62:65], v[150:153], v[186:189], v[62:65]
	v_mfma_f32_16x16x32_bf16 v[58:61], v[158:161], v[186:189], v[58:61]
	v_mfma_f32_16x16x32_bf16 v[54:57], v[150:153], v[190:193], v[54:57]
	v_mfma_f32_16x16x32_bf16 v[50:53], v[158:161], v[190:193], v[50:53]
	s_setprio 0
	s_barrier
	s_mov_b32 m0, s21
	ds_read_b128 v[162:165], v221 offset:16384
	ds_read_b128 v[166:169], v221 offset:18432
	ds_read_b128 v[170:173], v222 offset:16384
	ds_read_b128 v[174:177], v222 offset:18432
	ds_read_b128 v[178:181], v221 offset:20480
	ds_read_b128 v[182:185], v221 offset:22528
	ds_read_b128 v[186:189], v222 offset:20480
	ds_read_b128 v[190:193], v222 offset:22528
	buffer_load_dwordx4 v208, s[4:7], s60 offen lds
	s_mov_b32 m0, s22
	s_add_i32 s62, s60, 0x40000
	buffer_load_dwordx4 v210, s[4:7], s60 offen lds
	s_mov_b32 m0, s23
	s_nop 0
	buffer_load_dwordx4 v208, s[4:7], s62 offen lds
	s_mov_b32 m0, s24
	s_nop 0
	buffer_load_dwordx4 v210, s[4:7], s62 offen lds
	s_mov_b32 m0, s20
	s_nop 0
	buffer_load_dwordx4 v207, s[4:7], s61 offen lds
	s_mov_b32 m0, s25
	s_nop 0
	buffer_load_dwordx4 v209, s[4:7], s61 offen lds
	s_waitcnt vmcnt(8)
	s_waitcnt lgkmcnt(0)
	s_setprio 1
	s_barrier
	v_mfma_f32_16x16x32_bf16 v[78:81], v[130:133], v[162:165], v[78:81]
	v_mfma_f32_16x16x32_bf16 v[46:49], v[138:141], v[162:165], v[46:49]
	v_mfma_f32_16x16x32_bf16 v[42:45], v[130:133], v[166:169], v[42:45]
	v_mfma_f32_16x16x32_bf16 v[38:41], v[138:141], v[166:169], v[38:41]
	v_mfma_f32_16x16x32_bf16 v[34:37], v[130:133], v[178:181], v[34:37]
	v_mfma_f32_16x16x32_bf16 v[30:33], v[138:141], v[178:181], v[30:33]
	v_mfma_f32_16x16x32_bf16 v[26:29], v[130:133], v[182:185], v[26:29]
	v_mfma_f32_16x16x32_bf16 v[22:25], v[138:141], v[182:185], v[22:25]
	v_mfma_f32_16x16x32_bf16 v[78:81], v[134:137], v[170:173], v[78:81]
	v_mfma_f32_16x16x32_bf16 v[46:49], v[142:145], v[170:173], v[46:49]
	v_mfma_f32_16x16x32_bf16 v[42:45], v[134:137], v[174:177], v[42:45]
	v_mfma_f32_16x16x32_bf16 v[38:41], v[142:145], v[174:177], v[38:41]
	v_mfma_f32_16x16x32_bf16 v[34:37], v[134:137], v[186:189], v[34:37]
	v_mfma_f32_16x16x32_bf16 v[30:33], v[142:145], v[186:189], v[30:33]
	v_mfma_f32_16x16x32_bf16 v[26:29], v[134:137], v[190:193], v[26:29]
	v_mfma_f32_16x16x32_bf16 v[22:25], v[142:145], v[190:193], v[22:25]
	v_mfma_f32_16x16x32_bf16 v[18:21], v[146:149], v[162:165], v[18:21]
	v_mfma_f32_16x16x32_bf16 v[14:17], v[154:157], v[162:165], v[14:17]
	v_mfma_f32_16x16x32_bf16 v[10:13], v[146:149], v[166:169], v[10:13]
	v_mfma_f32_16x16x32_bf16 v[6:9], v[154:157], v[166:169], v[6:9]
	v_mfma_f32_16x16x32_bf16 v[2:5], v[146:149], v[178:181], v[2:5]
	v_mfma_f32_16x16x32_bf16 v[126:129], v[154:157], v[178:181], v[126:129]
	v_mfma_f32_16x16x32_bf16 v[122:125], v[146:149], v[182:185], v[122:125]
	v_mfma_f32_16x16x32_bf16 v[118:121], v[154:157], v[182:185], v[118:121]
	v_mfma_f32_16x16x32_bf16 v[18:21], v[150:153], v[170:173], v[18:21]
	v_mfma_f32_16x16x32_bf16 v[14:17], v[158:161], v[170:173], v[14:17]
	v_mfma_f32_16x16x32_bf16 v[10:13], v[150:153], v[174:177], v[10:13]
	v_mfma_f32_16x16x32_bf16 v[6:9], v[158:161], v[174:177], v[6:9]
	v_mfma_f32_16x16x32_bf16 v[2:5], v[150:153], v[186:189], v[2:5]
	v_mfma_f32_16x16x32_bf16 v[126:129], v[158:161], v[186:189], v[126:129]
	v_mfma_f32_16x16x32_bf16 v[122:125], v[150:153], v[190:193], v[122:125]
	v_mfma_f32_16x16x32_bf16 v[118:121], v[158:161], v[190:193], v[118:121]
	s_setprio 0
	s_barrier
	ds_read_b128 v[130:133], v194
	ds_read_b128 v[134:137], v224
	ds_read_b128 v[138:141], v225
	ds_read_b128 v[142:145], v228
	ds_read_b128 v[146:149], v229
	ds_read_b128 v[150:153], v230
	ds_read_b128 v[154:157], v231
	ds_read_b128 v[158:161], v233
	s_addk_i32 s61, 0x2000
	s_mov_b32 m0, s26
	ds_read_b128 v[162:165], v221 offset:32768
	ds_read_b128 v[166:169], v221 offset:34816
	ds_read_b128 v[170:173], v222 offset:32768
	ds_read_b128 v[174:177], v222 offset:34816
	ds_read_b128 v[178:181], v221 offset:36864
	ds_read_b128 v[182:185], v221 offset:38912
	ds_read_b128 v[186:189], v222 offset:36864
	ds_read_b128 v[190:193], v222 offset:38912
	buffer_load_dwordx4 v207, s[4:7], s61 offen lds
	s_mov_b32 m0, s27
	s_nop 0
	buffer_load_dwordx4 v209, s[4:7], s61 offen lds
	s_waitcnt vmcnt(8)
	s_waitcnt lgkmcnt(0)
	s_setprio 1
	s_barrier
	v_mfma_f32_16x16x32_bf16 v[114:117], v[130:133], v[162:165], v[114:117]
	v_mfma_f32_16x16x32_bf16 v[110:113], v[138:141], v[162:165], v[110:113]
	v_mfma_f32_16x16x32_bf16 v[106:109], v[130:133], v[166:169], v[106:109]
	v_mfma_f32_16x16x32_bf16 v[102:105], v[138:141], v[166:169], v[102:105]
	v_mfma_f32_16x16x32_bf16 v[98:101], v[130:133], v[178:181], v[98:101]
	v_mfma_f32_16x16x32_bf16 v[94:97], v[138:141], v[178:181], v[94:97]
	v_mfma_f32_16x16x32_bf16 v[90:93], v[130:133], v[182:185], v[90:93]
	v_mfma_f32_16x16x32_bf16 v[86:89], v[138:141], v[182:185], v[86:89]
	v_mfma_f32_16x16x32_bf16 v[114:117], v[134:137], v[170:173], v[114:117]
	v_mfma_f32_16x16x32_bf16 v[110:113], v[142:145], v[170:173], v[110:113]
	v_mfma_f32_16x16x32_bf16 v[106:109], v[134:137], v[174:177], v[106:109]
	v_mfma_f32_16x16x32_bf16 v[102:105], v[142:145], v[174:177], v[102:105]
	v_mfma_f32_16x16x32_bf16 v[98:101], v[134:137], v[186:189], v[98:101]
	v_mfma_f32_16x16x32_bf16 v[94:97], v[142:145], v[186:189], v[94:97]
	v_mfma_f32_16x16x32_bf16 v[90:93], v[134:137], v[190:193], v[90:93]
	v_mfma_f32_16x16x32_bf16 v[86:89], v[142:145], v[190:193], v[86:89]
	v_mfma_f32_16x16x32_bf16 v[82:85], v[146:149], v[162:165], v[82:85]
	v_mfma_f32_16x16x32_bf16 v[74:77], v[154:157], v[162:165], v[74:77]
	v_mfma_f32_16x16x32_bf16 v[70:73], v[146:149], v[166:169], v[70:73]
	v_mfma_f32_16x16x32_bf16 v[66:69], v[154:157], v[166:169], v[66:69]
	v_mfma_f32_16x16x32_bf16 v[62:65], v[146:149], v[178:181], v[62:65]
	v_mfma_f32_16x16x32_bf16 v[58:61], v[154:157], v[178:181], v[58:61]
	v_mfma_f32_16x16x32_bf16 v[54:57], v[146:149], v[182:185], v[54:57]
	v_mfma_f32_16x16x32_bf16 v[50:53], v[154:157], v[182:185], v[50:53]
	v_mfma_f32_16x16x32_bf16 v[82:85], v[150:153], v[170:173], v[82:85]
	v_mfma_f32_16x16x32_bf16 v[74:77], v[158:161], v[170:173], v[74:77]
	v_mfma_f32_16x16x32_bf16 v[70:73], v[150:153], v[174:177], v[70:73]
	v_mfma_f32_16x16x32_bf16 v[66:69], v[158:161], v[174:177], v[66:69]
	v_mfma_f32_16x16x32_bf16 v[62:65], v[150:153], v[186:189], v[62:65]
	v_mfma_f32_16x16x32_bf16 v[58:61], v[158:161], v[186:189], v[58:61]
	v_mfma_f32_16x16x32_bf16 v[54:57], v[150:153], v[190:193], v[54:57]
	v_mfma_f32_16x16x32_bf16 v[50:53], v[158:161], v[190:193], v[50:53]
	s_setprio 0
	s_barrier
	s_mov_b32 m0, s29
	s_add_i32 s61, s60, 0x80
	ds_read_b128 v[162:165], v221 offset:49152
	ds_read_b128 v[166:169], v221 offset:51200
	ds_read_b128 v[170:173], v222 offset:49152
	ds_read_b128 v[174:177], v222 offset:51200
	ds_read_b128 v[178:181], v221 offset:53248
	ds_read_b128 v[182:185], v221 offset:55296
	ds_read_b128 v[186:189], v222 offset:53248
	ds_read_b128 v[190:193], v222 offset:55296
	buffer_load_dwordx4 v208, s[4:7], s61 offen lds
	s_mov_b32 m0, s30
	s_add_i32 s60, s60, 0x40080
	buffer_load_dwordx4 v210, s[4:7], s61 offen lds
	s_mov_b32 m0, s35
	s_nop 0
	buffer_load_dwordx4 v208, s[4:7], s60 offen lds
	s_mov_b32 m0, s36
	s_nop 0
	buffer_load_dwordx4 v210, s[4:7], s60 offen lds
	s_mov_b32 m0, s31
	s_nop 0
	buffer_load_dwordx4 v207, s[4:7], s59 offen lds
	s_mov_b32 m0, s34
	s_nop 0
	buffer_load_dwordx4 v209, s[4:7], s59 offen lds
	s_waitcnt vmcnt(8)
	s_waitcnt lgkmcnt(0)
	s_setprio 1
	s_barrier
	v_mfma_f32_16x16x32_bf16 v[78:81], v[130:133], v[162:165], v[78:81]
	v_mfma_f32_16x16x32_bf16 v[46:49], v[138:141], v[162:165], v[46:49]
	v_mfma_f32_16x16x32_bf16 v[42:45], v[130:133], v[166:169], v[42:45]
	v_mfma_f32_16x16x32_bf16 v[38:41], v[138:141], v[166:169], v[38:41]
	v_mfma_f32_16x16x32_bf16 v[34:37], v[130:133], v[178:181], v[34:37]
	v_mfma_f32_16x16x32_bf16 v[30:33], v[138:141], v[178:181], v[30:33]
	v_mfma_f32_16x16x32_bf16 v[26:29], v[130:133], v[182:185], v[26:29]
	v_mfma_f32_16x16x32_bf16 v[22:25], v[138:141], v[182:185], v[22:25]
	v_mfma_f32_16x16x32_bf16 v[78:81], v[134:137], v[170:173], v[78:81]
	v_mfma_f32_16x16x32_bf16 v[46:49], v[142:145], v[170:173], v[46:49]
	v_mfma_f32_16x16x32_bf16 v[42:45], v[134:137], v[174:177], v[42:45]
	v_mfma_f32_16x16x32_bf16 v[38:41], v[142:145], v[174:177], v[38:41]
	v_mfma_f32_16x16x32_bf16 v[34:37], v[134:137], v[186:189], v[34:37]
	v_mfma_f32_16x16x32_bf16 v[30:33], v[142:145], v[186:189], v[30:33]
	v_mfma_f32_16x16x32_bf16 v[26:29], v[134:137], v[190:193], v[26:29]
	v_mfma_f32_16x16x32_bf16 v[22:25], v[142:145], v[190:193], v[22:25]
	v_mfma_f32_16x16x32_bf16 v[18:21], v[146:149], v[162:165], v[18:21]
	v_mfma_f32_16x16x32_bf16 v[14:17], v[154:157], v[162:165], v[14:17]
	v_mfma_f32_16x16x32_bf16 v[10:13], v[146:149], v[166:169], v[10:13]
	v_mfma_f32_16x16x32_bf16 v[6:9], v[154:157], v[166:169], v[6:9]
	v_mfma_f32_16x16x32_bf16 v[2:5], v[146:149], v[178:181], v[2:5]
	v_mfma_f32_16x16x32_bf16 v[126:129], v[154:157], v[178:181], v[126:129]
	v_mfma_f32_16x16x32_bf16 v[122:125], v[146:149], v[182:185], v[122:125]
	v_mfma_f32_16x16x32_bf16 v[118:121], v[154:157], v[182:185], v[118:121]
	v_mfma_f32_16x16x32_bf16 v[18:21], v[150:153], v[170:173], v[18:21]
	v_mfma_f32_16x16x32_bf16 v[14:17], v[158:161], v[170:173], v[14:17]
	v_mfma_f32_16x16x32_bf16 v[10:13], v[150:153], v[174:177], v[10:13]
	v_mfma_f32_16x16x32_bf16 v[6:9], v[158:161], v[174:177], v[6:9]
	v_mfma_f32_16x16x32_bf16 v[2:5], v[150:153], v[186:189], v[2:5]
	v_mfma_f32_16x16x32_bf16 v[126:129], v[158:161], v[186:189], v[126:129]
	v_mfma_f32_16x16x32_bf16 v[122:125], v[150:153], v[190:193], v[122:125]
	v_mfma_f32_16x16x32_bf16 v[118:121], v[158:161], v[190:193], v[118:121]
	s_setprio 0
	s_barrier
	s_add_i32 s58, s58, 2
	s_addk_i32 s33, 0x100
	s_addk_i32 s57, 0x100
	s_cmp_gt_u32 s58, 13
	s_cbranch_scc0 .LBB0_233
	s_and_b64 vcc, exec, s[16:17]
	s_cbranch_vccz .LBB0_236
	s_barrier

.LBB0_546:
	ds_read_b128 v[130:133], v211
	ds_read_b128 v[134:137], v212
	ds_read_b128 v[138:141], v213
	ds_read_b128 v[142:145], v214
	ds_read_b128 v[146:149], v215
	ds_read_b128 v[150:153], v216
	ds_read_b128 v[154:157], v217
	ds_read_b128 v[158:161], v218
	s_add_i32 s4, s62, 0x80
	s_cmp_eq_u32 s63, s78
	s_cselect_b32 s84, s64, s4
	s_cselect_b32 s82, s33, s59
	s_cselect_b32 s81, s65, s61
	s_cselect_b32 s80, s56, s60
	s_add_i32 s79, s84, 0x80
	s_add_i32 s83, s60, s62
	s_mov_b32 s4, s70
	s_mov_b32 m0, s43
	ds_read_b128 v[162:165], v219
	ds_read_b128 v[166:169], v219 offset:2048
	ds_read_b128 v[170:173], v220
	ds_read_b128 v[174:177], v220 offset:2048
	ds_read_b128 v[178:181], v219 offset:4096
	ds_read_b128 v[182:185], v219 offset:6144
	ds_read_b128 v[186:189], v220 offset:4096
	ds_read_b128 v[190:193], v220 offset:6144
	buffer_load_dwordx4 v194, s[4:7], s83 offen lds
	s_mov_b32 m0, s44
	s_nop 0
	buffer_load_dwordx4 v222, s[4:7], s83 offen lds
	s_waitcnt vmcnt(8)
	s_waitcnt lgkmcnt(0)
	s_setprio 1
	s_barrier
	v_mfma_f32_16x16x32_bf16 v[126:129], v[130:133], v[162:165], v[126:129]
	v_mfma_f32_16x16x32_bf16 v[122:125], v[138:141], v[162:165], v[122:125]
	v_mfma_f32_16x16x32_bf16 v[118:121], v[130:133], v[166:169], v[118:121]
	v_mfma_f32_16x16x32_bf16 v[114:117], v[138:141], v[166:169], v[114:117]
	v_mfma_f32_16x16x32_bf16 v[110:113], v[130:133], v[178:181], v[110:113]
	v_mfma_f32_16x16x32_bf16 v[106:109], v[138:141], v[178:181], v[106:109]
	v_mfma_f32_16x16x32_bf16 v[102:105], v[130:133], v[182:185], v[102:105]
	v_mfma_f32_16x16x32_bf16 v[98:101], v[138:141], v[182:185], v[98:101]
	v_mfma_f32_16x16x32_bf16 v[126:129], v[134:137], v[170:173], v[126:129]
	v_mfma_f32_16x16x32_bf16 v[122:125], v[142:145], v[170:173], v[122:125]
	v_mfma_f32_16x16x32_bf16 v[118:121], v[134:137], v[174:177], v[118:121]
	v_mfma_f32_16x16x32_bf16 v[114:117], v[142:145], v[174:177], v[114:117]
	v_mfma_f32_16x16x32_bf16 v[110:113], v[134:137], v[186:189], v[110:113]
	v_mfma_f32_16x16x32_bf16 v[106:109], v[142:145], v[186:189], v[106:109]
	v_mfma_f32_16x16x32_bf16 v[102:105], v[134:137], v[190:193], v[102:105]
	v_mfma_f32_16x16x32_bf16 v[98:101], v[142:145], v[190:193], v[98:101]
	v_mfma_f32_16x16x32_bf16 v[94:97], v[146:149], v[162:165], v[94:97]
	v_mfma_f32_16x16x32_bf16 v[90:93], v[154:157], v[162:165], v[90:93]
	v_mfma_f32_16x16x32_bf16 v[86:89], v[146:149], v[166:169], v[86:89]
	v_mfma_f32_16x16x32_bf16 v[82:85], v[154:157], v[166:169], v[82:85]
	v_mfma_f32_16x16x32_bf16 v[78:81], v[146:149], v[178:181], v[78:81]
	v_mfma_f32_16x16x32_bf16 v[74:77], v[154:157], v[178:181], v[74:77]
	v_mfma_f32_16x16x32_bf16 v[70:73], v[146:149], v[182:185], v[70:73]
	v_mfma_f32_16x16x32_bf16 v[66:69], v[154:157], v[182:185], v[66:69]
	v_mfma_f32_16x16x32_bf16 v[94:97], v[150:153], v[170:173], v[94:97]
	v_mfma_f32_16x16x32_bf16 v[90:93], v[158:161], v[170:173], v[90:93]
	v_mfma_f32_16x16x32_bf16 v[86:89], v[150:153], v[174:177], v[86:89]
	v_mfma_f32_16x16x32_bf16 v[82:85], v[158:161], v[174:177], v[82:85]
	v_mfma_f32_16x16x32_bf16 v[78:81], v[150:153], v[186:189], v[78:81]
	v_mfma_f32_16x16x32_bf16 v[74:77], v[158:161], v[186:189], v[74:77]
	v_mfma_f32_16x16x32_bf16 v[70:73], v[150:153], v[190:193], v[70:73]
	v_mfma_f32_16x16x32_bf16 v[66:69], v[158:161], v[190:193], v[66:69]
	s_setprio 0
	s_barrier
	s_cmp_eq_u32 s82, 0
	s_cselect_b64 s[82:83], -1, 0
	v_cndmask_b32_e64 v233, v200, 0, s[82:83]
	s_mov_b32 m0, s25
	v_sub_u32_e32 v233, v201, v233
	v_cndmask_b32_e64 v234, v203, 0, s[82:83]
	ds_read_b128 v[162:165], v219 offset:16384
	ds_read_b128 v[166:169], v219 offset:18432
	ds_read_b128 v[170:173], v220 offset:16384
	ds_read_b128 v[174:177], v220 offset:18432
	ds_read_b128 v[178:181], v219 offset:20480
	ds_read_b128 v[182:185], v219 offset:22528
	ds_read_b128 v[186:189], v220 offset:20480
	ds_read_b128 v[190:193], v220 offset:22528
	buffer_load_dwordx4 v233, s[4:7], s81 offen lds
	v_sub_u32_e32 v234, v204, v234
	s_mov_b32 m0, s26
	s_add_i32 s85, s81, s80
	buffer_load_dwordx4 v234, s[4:7], s81 offen lds
	s_mov_b32 m0, s27
	v_cndmask_b32_e64 v235, v205, 0, s[82:83]
	buffer_load_dwordx4 v233, s[4:7], s85 offen lds
	s_mov_b32 m0, s28
	v_sub_u32_e32 v235, v1, v235
	buffer_load_dwordx4 v234, s[4:7], s85 offen lds
	s_mov_b32 m0, s24
	v_cndmask_b32_e64 v236, v206, 0, s[82:83]
	buffer_load_dwordx4 v235, s[4:7], s84 offen lds
	v_sub_u32_e32 v236, v202, v236
	s_mov_b32 m0, s29
	s_nop 0
	buffer_load_dwordx4 v236, s[4:7], s84 offen lds
	s_waitcnt vmcnt(8)
	s_waitcnt lgkmcnt(0)
	s_setprio 1
	s_barrier
	v_mfma_f32_16x16x32_bf16 v[62:65], v[130:133], v[162:165], v[62:65]
	v_mfma_f32_16x16x32_bf16 v[58:61], v[138:141], v[162:165], v[58:61]
	v_mfma_f32_16x16x32_bf16 v[54:57], v[130:133], v[166:169], v[54:57]
	v_mfma_f32_16x16x32_bf16 v[50:53], v[138:141], v[166:169], v[50:53]
	v_mfma_f32_16x16x32_bf16 v[46:49], v[130:133], v[178:181], v[46:49]
	v_mfma_f32_16x16x32_bf16 v[42:45], v[138:141], v[178:181], v[42:45]
	v_mfma_f32_16x16x32_bf16 v[38:41], v[130:133], v[182:185], v[38:41]
	v_mfma_f32_16x16x32_bf16 v[34:37], v[138:141], v[182:185], v[34:37]
	v_mfma_f32_16x16x32_bf16 v[62:65], v[134:137], v[170:173], v[62:65]
	v_mfma_f32_16x16x32_bf16 v[58:61], v[142:145], v[170:173], v[58:61]
	v_mfma_f32_16x16x32_bf16 v[54:57], v[134:137], v[174:177], v[54:57]
	v_mfma_f32_16x16x32_bf16 v[50:53], v[142:145], v[174:177], v[50:53]
	v_mfma_f32_16x16x32_bf16 v[46:49], v[134:137], v[186:189], v[46:49]
	v_mfma_f32_16x16x32_bf16 v[42:45], v[142:145], v[186:189], v[42:45]
	v_mfma_f32_16x16x32_bf16 v[38:41], v[134:137], v[190:193], v[38:41]
	v_mfma_f32_16x16x32_bf16 v[34:37], v[142:145], v[190:193], v[34:37]
	v_mfma_f32_16x16x32_bf16 v[30:33], v[146:149], v[162:165], v[30:33]
	v_mfma_f32_16x16x32_bf16 v[26:29], v[154:157], v[162:165], v[26:29]
	v_mfma_f32_16x16x32_bf16 v[22:25], v[146:149], v[166:169], v[22:25]
	v_mfma_f32_16x16x32_bf16 v[18:21], v[154:157], v[166:169], v[18:21]
	v_mfma_f32_16x16x32_bf16 v[14:17], v[146:149], v[178:181], v[14:17]
	v_mfma_f32_16x16x32_bf16 v[10:13], v[154:157], v[178:181], v[10:13]
	v_mfma_f32_16x16x32_bf16 v[6:9], v[146:149], v[182:185], v[6:9]
	v_mfma_f32_16x16x32_bf16 v[2:5], v[154:157], v[182:185], v[2:5]
	v_mfma_f32_16x16x32_bf16 v[30:33], v[150:153], v[170:173], v[30:33]
	v_mfma_f32_16x16x32_bf16 v[26:29], v[158:161], v[170:173], v[26:29]
	v_mfma_f32_16x16x32_bf16 v[22:25], v[150:153], v[174:177], v[22:25]
	v_mfma_f32_16x16x32_bf16 v[18:21], v[158:161], v[174:177], v[18:21]
	v_mfma_f32_16x16x32_bf16 v[14:17], v[150:153], v[186:189], v[14:17]
	v_mfma_f32_16x16x32_bf16 v[10:13], v[158:161], v[186:189], v[10:13]
	v_mfma_f32_16x16x32_bf16 v[6:9], v[150:153], v[190:193], v[6:9]
	v_mfma_f32_16x16x32_bf16 v[2:5], v[158:161], v[190:193], v[2:5]
	s_setprio 0
	s_barrier
	ds_read_b128 v[130:133], v223
	ds_read_b128 v[134:137], v224
	ds_read_b128 v[138:141], v225
	ds_read_b128 v[142:145], v227
	ds_read_b128 v[146:149], v228
	ds_read_b128 v[150:153], v229
	ds_read_b128 v[154:157], v230
	ds_read_b128 v[158:161], v231
	s_add_i32 s84, s84, s80
	s_mov_b32 m0, s30
	ds_read_b128 v[162:165], v219 offset:32768
	ds_read_b128 v[166:169], v219 offset:34816
	ds_read_b128 v[170:173], v220 offset:32768
	ds_read_b128 v[174:177], v220 offset:34816
	ds_read_b128 v[178:181], v219 offset:36864
	ds_read_b128 v[182:185], v219 offset:38912
	ds_read_b128 v[186:189], v220 offset:36864
	ds_read_b128 v[190:193], v220 offset:38912
	buffer_load_dwordx4 v235, s[4:7], s84 offen lds
	s_mov_b32 m0, s31
	s_nop 0
	buffer_load_dwordx4 v236, s[4:7], s84 offen lds
	s_waitcnt vmcnt(8)
	s_waitcnt lgkmcnt(0)
	s_setprio 1
	s_barrier
	v_mfma_f32_16x16x32_bf16 v[126:129], v[130:133], v[162:165], v[126:129]
	v_mfma_f32_16x16x32_bf16 v[122:125], v[138:141], v[162:165], v[122:125]
	v_mfma_f32_16x16x32_bf16 v[118:121], v[130:133], v[166:169], v[118:121]
	v_mfma_f32_16x16x32_bf16 v[114:117], v[138:141], v[166:169], v[114:117]
	v_mfma_f32_16x16x32_bf16 v[110:113], v[130:133], v[178:181], v[110:113]
	v_mfma_f32_16x16x32_bf16 v[106:109], v[138:141], v[178:181], v[106:109]
	v_mfma_f32_16x16x32_bf16 v[102:105], v[130:133], v[182:185], v[102:105]
	v_mfma_f32_16x16x32_bf16 v[98:101], v[138:141], v[182:185], v[98:101]
	v_mfma_f32_16x16x32_bf16 v[126:129], v[134:137], v[170:173], v[126:129]
	v_mfma_f32_16x16x32_bf16 v[122:125], v[142:145], v[170:173], v[122:125]
	v_mfma_f32_16x16x32_bf16 v[118:121], v[134:137], v[174:177], v[118:121]
	v_mfma_f32_16x16x32_bf16 v[114:117], v[142:145], v[174:177], v[114:117]
	v_mfma_f32_16x16x32_bf16 v[110:113], v[134:137], v[186:189], v[110:113]
	v_mfma_f32_16x16x32_bf16 v[106:109], v[142:145], v[186:189], v[106:109]
	v_mfma_f32_16x16x32_bf16 v[102:105], v[134:137], v[190:193], v[102:105]
	v_mfma_f32_16x16x32_bf16 v[98:101], v[142:145], v[190:193], v[98:101]
	v_mfma_f32_16x16x32_bf16 v[94:97], v[146:149], v[162:165], v[94:97]
	v_mfma_f32_16x16x32_bf16 v[90:93], v[154:157], v[162:165], v[90:93]
	v_mfma_f32_16x16x32_bf16 v[86:89], v[146:149], v[166:169], v[86:89]
	v_mfma_f32_16x16x32_bf16 v[82:85], v[154:157], v[166:169], v[82:85]
	v_mfma_f32_16x16x32_bf16 v[78:81], v[146:149], v[178:181], v[78:81]
	v_mfma_f32_16x16x32_bf16 v[74:77], v[154:157], v[178:181], v[74:77]
	v_mfma_f32_16x16x32_bf16 v[70:73], v[146:149], v[182:185], v[70:73]
	v_mfma_f32_16x16x32_bf16 v[66:69], v[154:157], v[182:185], v[66:69]
	v_mfma_f32_16x16x32_bf16 v[94:97], v[150:153], v[170:173], v[94:97]
	v_mfma_f32_16x16x32_bf16 v[90:93], v[158:161], v[170:173], v[90:93]
	v_mfma_f32_16x16x32_bf16 v[86:89], v[150:153], v[174:177], v[86:89]
	v_mfma_f32_16x16x32_bf16 v[82:85], v[158:161], v[174:177], v[82:85]
	v_mfma_f32_16x16x32_bf16 v[78:81], v[150:153], v[186:189], v[78:81]
	v_mfma_f32_16x16x32_bf16 v[74:77], v[158:161], v[186:189], v[74:77]
	v_mfma_f32_16x16x32_bf16 v[70:73], v[150:153], v[190:193], v[70:73]
	v_mfma_f32_16x16x32_bf16 v[66:69], v[158:161], v[190:193], v[66:69]
	s_setprio 0
	s_barrier
	s_mov_b32 m0, s36
	s_addk_i32 s81, 0x80
	ds_read_b128 v[162:165], v219 offset:49152
	ds_read_b128 v[166:169], v219 offset:51200
	ds_read_b128 v[170:173], v220 offset:49152
	ds_read_b128 v[174:177], v220 offset:51200
	ds_read_b128 v[178:181], v219 offset:53248
	ds_read_b128 v[182:185], v219 offset:55296
	ds_read_b128 v[186:189], v220 offset:53248
	ds_read_b128 v[190:193], v220 offset:55296
	buffer_load_dwordx4 v233, s[4:7], s81 offen lds
	s_mov_b32 m0, s37
	s_nop 0
	buffer_load_dwordx4 v234, s[4:7], s81 offen lds
	s_add_i32 s81, s81, s80
	s_mov_b32 m0, s40
	s_nop 0
	buffer_load_dwordx4 v233, s[4:7], s81 offen lds
	s_mov_b32 m0, s41
	s_nop 0
	buffer_load_dwordx4 v234, s[4:7], s81 offen lds
	s_mov_b32 m0, s38
	s_nop 0
	buffer_load_dwordx4 v235, s[4:7], s79 offen lds
	s_mov_b32 m0, s39
	s_nop 0
	buffer_load_dwordx4 v236, s[4:7], s79 offen lds
	s_waitcnt vmcnt(8)
	s_waitcnt lgkmcnt(0)
	s_setprio 1
	s_barrier
	v_mfma_f32_16x16x32_bf16 v[62:65], v[130:133], v[162:165], v[62:65]
	v_mfma_f32_16x16x32_bf16 v[58:61], v[138:141], v[162:165], v[58:61]
	v_mfma_f32_16x16x32_bf16 v[54:57], v[130:133], v[166:169], v[54:57]
	v_mfma_f32_16x16x32_bf16 v[50:53], v[138:141], v[166:169], v[50:53]
	v_mfma_f32_16x16x32_bf16 v[46:49], v[130:133], v[178:181], v[46:49]
	v_mfma_f32_16x16x32_bf16 v[42:45], v[138:141], v[178:181], v[42:45]
	v_mfma_f32_16x16x32_bf16 v[38:41], v[130:133], v[182:185], v[38:41]
	v_mfma_f32_16x16x32_bf16 v[34:37], v[138:141], v[182:185], v[34:37]
	v_mfma_f32_16x16x32_bf16 v[62:65], v[134:137], v[170:173], v[62:65]
	v_mfma_f32_16x16x32_bf16 v[58:61], v[142:145], v[170:173], v[58:61]
	v_mfma_f32_16x16x32_bf16 v[54:57], v[134:137], v[174:177], v[54:57]
	v_mfma_f32_16x16x32_bf16 v[50:53], v[142:145], v[174:177], v[50:53]
	v_mfma_f32_16x16x32_bf16 v[46:49], v[134:137], v[186:189], v[46:49]
	v_mfma_f32_16x16x32_bf16 v[42:45], v[142:145], v[186:189], v[42:45]
	v_mfma_f32_16x16x32_bf16 v[38:41], v[134:137], v[190:193], v[38:41]
	v_mfma_f32_16x16x32_bf16 v[34:37], v[142:145], v[190:193], v[34:37]
	v_mfma_f32_16x16x32_bf16 v[30:33], v[146:149], v[162:165], v[30:33]
	v_mfma_f32_16x16x32_bf16 v[26:29], v[154:157], v[162:165], v[26:29]
	v_mfma_f32_16x16x32_bf16 v[22:25], v[146:149], v[166:169], v[22:25]
	v_mfma_f32_16x16x32_bf16 v[18:21], v[154:157], v[166:169], v[18:21]
	v_mfma_f32_16x16x32_bf16 v[14:17], v[146:149], v[178:181], v[14:17]
	v_mfma_f32_16x16x32_bf16 v[10:13], v[154:157], v[178:181], v[10:13]
	v_mfma_f32_16x16x32_bf16 v[6:9], v[146:149], v[182:185], v[6:9]
	v_mfma_f32_16x16x32_bf16 v[2:5], v[154:157], v[182:185], v[2:5]
	v_mfma_f32_16x16x32_bf16 v[30:33], v[150:153], v[170:173], v[30:33]
	v_mfma_f32_16x16x32_bf16 v[26:29], v[158:161], v[170:173], v[26:29]
	v_mfma_f32_16x16x32_bf16 v[22:25], v[150:153], v[174:177], v[22:25]
	v_mfma_f32_16x16x32_bf16 v[18:21], v[158:161], v[174:177], v[18:21]
	v_mfma_f32_16x16x32_bf16 v[14:17], v[150:153], v[186:189], v[14:17]
	v_mfma_f32_16x16x32_bf16 v[10:13], v[158:161], v[186:189], v[10:13]
	v_mfma_f32_16x16x32_bf16 v[6:9], v[150:153], v[190:193], v[6:9]
	v_mfma_f32_16x16x32_bf16 v[2:5], v[158:161], v[190:193], v[2:5]
	s_setprio 0
	s_barrier
	s_add_i32 s4, s78, 2
	s_addk_i32 s62, 0x100
	s_addk_i32 s61, 0x100
	s_cmp_ge_u32 s78, s63
	s_mov_b32 s78, s4
	s_cbranch_scc0 .LBB0_546
	s_and_b64 vcc, exec, s[12:13]
	s_cbranch_vccz .LBB0_549
	s_barrier

.LBB0_841:
	ds_read_b128 v[130:133], v240
	ds_read_b128 v[134:137], v241
	ds_read_b128 v[138:141], v242
	ds_read_b128 v[142:145], v243
	ds_read_b128 v[146:149], v244
	ds_read_b128 v[150:153], v245
	ds_read_b128 v[154:157], v246
	ds_read_b128 v[158:161], v247
	s_add_i32 s8, s42, s5
	s_add_i32 s19, s34, s5
	s_add_i32 s18, s8, 0x800
	s_addk_i32 s19, 0x800
	s_cmp_eq_u32 s5, 0
	s_cselect_b32 s20, s0, s18
	s_cselect_b32 s19, s1, s19
	s_add_i32 s18, s20, 0x80
	s_add_i32 s21, s8, 0x40780
	s_mov_b32 s8, s70
	s_mov_b32 m0, s52
	ds_read_b128 v[162:165], v248
	ds_read_b128 v[166:169], v248 offset:2048
	ds_read_b128 v[170:173], v249
	ds_read_b128 v[174:177], v249 offset:2048
	ds_read_b128 v[178:181], v248 offset:4096
	ds_read_b128 v[182:185], v248 offset:6144
	ds_read_b128 v[186:189], v249 offset:4096
	ds_read_b128 v[190:193], v249 offset:6144
	buffer_load_dwordx4 v1, s[8:11], s21 offen lds
	s_mov_b32 m0, s53
	s_nop 0
	buffer_load_dwordx4 v234, s[8:11], s21 offen lds
	s_waitcnt vmcnt(8)
	s_waitcnt lgkmcnt(0)
	s_setprio 1
	s_barrier
	v_mfma_f32_16x16x32_bf16 v[74:77], v[130:133], v[162:165], v[74:77]
	v_mfma_f32_16x16x32_bf16 v[70:73], v[138:141], v[162:165], v[70:73]
	v_mfma_f32_16x16x32_bf16 v[66:69], v[130:133], v[166:169], v[66:69]
	v_mfma_f32_16x16x32_bf16 v[82:85], v[138:141], v[166:169], v[82:85]
	v_mfma_f32_16x16x32_bf16 v[78:81], v[130:133], v[178:181], v[78:81]
	v_mfma_f32_16x16x32_bf16 v[90:93], v[138:141], v[178:181], v[90:93]
	v_mfma_f32_16x16x32_bf16 v[86:89], v[130:133], v[182:185], v[86:89]
	v_mfma_f32_16x16x32_bf16 v[102:105], v[138:141], v[182:185], v[102:105]
	v_mfma_f32_16x16x32_bf16 v[74:77], v[134:137], v[170:173], v[74:77]
	v_mfma_f32_16x16x32_bf16 v[70:73], v[142:145], v[170:173], v[70:73]
	v_mfma_f32_16x16x32_bf16 v[66:69], v[134:137], v[174:177], v[66:69]
	v_mfma_f32_16x16x32_bf16 v[82:85], v[142:145], v[174:177], v[82:85]
	v_mfma_f32_16x16x32_bf16 v[78:81], v[134:137], v[186:189], v[78:81]
	v_mfma_f32_16x16x32_bf16 v[90:93], v[142:145], v[186:189], v[90:93]
	v_mfma_f32_16x16x32_bf16 v[86:89], v[134:137], v[190:193], v[86:89]
	v_mfma_f32_16x16x32_bf16 v[102:105], v[142:145], v[190:193], v[102:105]
	v_mfma_f32_16x16x32_bf16 v[98:101], v[146:149], v[162:165], v[98:101]
	v_mfma_f32_16x16x32_bf16 v[94:97], v[154:157], v[162:165], v[94:97]
	v_mfma_f32_16x16x32_bf16 v[106:109], v[146:149], v[166:169], v[106:109]
	v_mfma_f32_16x16x32_bf16 v[110:113], v[154:157], v[166:169], v[110:113]
	v_mfma_f32_16x16x32_bf16 v[114:117], v[146:149], v[178:181], v[114:117]
	v_mfma_f32_16x16x32_bf16 v[118:121], v[154:157], v[178:181], v[118:121]
	v_mfma_f32_16x16x32_bf16 v[122:125], v[146:149], v[182:185], v[122:125]
	v_mfma_f32_16x16x32_bf16 v[126:129], v[154:157], v[182:185], v[126:129]
	v_mfma_f32_16x16x32_bf16 v[98:101], v[150:153], v[170:173], v[98:101]
	v_mfma_f32_16x16x32_bf16 v[94:97], v[158:161], v[170:173], v[94:97]
	v_mfma_f32_16x16x32_bf16 v[106:109], v[150:153], v[174:177], v[106:109]
	v_mfma_f32_16x16x32_bf16 v[110:113], v[158:161], v[174:177], v[110:113]
	v_mfma_f32_16x16x32_bf16 v[114:117], v[150:153], v[186:189], v[114:117]
	v_mfma_f32_16x16x32_bf16 v[118:121], v[158:161], v[186:189], v[118:121]
	v_mfma_f32_16x16x32_bf16 v[122:125], v[150:153], v[190:193], v[122:125]
	v_mfma_f32_16x16x32_bf16 v[126:129], v[158:161], v[190:193], v[126:129]
	s_setprio 0
	s_barrier
	s_mov_b32 m0, s29
	ds_read_b128 v[162:165], v248 offset:16384
	ds_read_b128 v[166:169], v248 offset:18432
	ds_read_b128 v[170:173], v249 offset:16384
	ds_read_b128 v[174:177], v249 offset:18432
	ds_read_b128 v[178:181], v248 offset:20480
	ds_read_b128 v[182:185], v248 offset:22528
	ds_read_b128 v[186:189], v249 offset:20480
	ds_read_b128 v[190:193], v249 offset:22528
	buffer_load_dwordx4 v233, s[8:11], s19 offen lds
	s_mov_b32 m0, s30
	s_add_i32 s21, s19, 0x40000
	buffer_load_dwordx4 v235, s[8:11], s19 offen lds
	s_mov_b32 m0, s31
	s_nop 0
	buffer_load_dwordx4 v233, s[8:11], s21 offen lds
	s_mov_b32 m0, s35
	s_nop 0
	buffer_load_dwordx4 v235, s[8:11], s21 offen lds
	s_mov_b32 m0, s28
	s_nop 0
	buffer_load_dwordx4 v1, s[8:11], s20 offen lds
	s_mov_b32 m0, s38
	s_nop 0
	buffer_load_dwordx4 v234, s[8:11], s20 offen lds
	s_waitcnt vmcnt(8)
	s_waitcnt lgkmcnt(0)
	s_setprio 1
	s_barrier
	v_mfma_f32_16x16x32_bf16 v[10:13], v[130:133], v[162:165], v[10:13]
	v_mfma_f32_16x16x32_bf16 v[6:9], v[138:141], v[162:165], v[6:9]
	v_mfma_f32_16x16x32_bf16 v[2:5], v[130:133], v[166:169], v[2:5]
	v_mfma_f32_16x16x32_bf16 v[18:21], v[138:141], v[166:169], v[18:21]
	v_mfma_f32_16x16x32_bf16 v[14:17], v[130:133], v[178:181], v[14:17]
	v_mfma_f32_16x16x32_bf16 v[26:29], v[138:141], v[178:181], v[26:29]
	v_mfma_f32_16x16x32_bf16 v[22:25], v[130:133], v[182:185], v[22:25]
	v_mfma_f32_16x16x32_bf16 v[38:41], v[138:141], v[182:185], v[38:41]
	v_mfma_f32_16x16x32_bf16 v[10:13], v[134:137], v[170:173], v[10:13]
	v_mfma_f32_16x16x32_bf16 v[6:9], v[142:145], v[170:173], v[6:9]
	v_mfma_f32_16x16x32_bf16 v[2:5], v[134:137], v[174:177], v[2:5]
	v_mfma_f32_16x16x32_bf16 v[18:21], v[142:145], v[174:177], v[18:21]
	v_mfma_f32_16x16x32_bf16 v[14:17], v[134:137], v[186:189], v[14:17]
	v_mfma_f32_16x16x32_bf16 v[26:29], v[142:145], v[186:189], v[26:29]
	v_mfma_f32_16x16x32_bf16 v[22:25], v[134:137], v[190:193], v[22:25]
	v_mfma_f32_16x16x32_bf16 v[38:41], v[142:145], v[190:193], v[38:41]
	v_mfma_f32_16x16x32_bf16 v[34:37], v[146:149], v[162:165], v[34:37]
	v_mfma_f32_16x16x32_bf16 v[30:33], v[154:157], v[162:165], v[30:33]
	v_mfma_f32_16x16x32_bf16 v[42:45], v[146:149], v[166:169], v[42:45]
	v_mfma_f32_16x16x32_bf16 v[46:49], v[154:157], v[166:169], v[46:49]
	v_mfma_f32_16x16x32_bf16 v[50:53], v[146:149], v[178:181], v[50:53]
	v_mfma_f32_16x16x32_bf16 v[54:57], v[154:157], v[178:181], v[54:57]
	v_mfma_f32_16x16x32_bf16 v[58:61], v[146:149], v[182:185], v[58:61]
	v_mfma_f32_16x16x32_bf16 v[62:65], v[154:157], v[182:185], v[62:65]
	v_mfma_f32_16x16x32_bf16 v[34:37], v[150:153], v[170:173], v[34:37]
	v_mfma_f32_16x16x32_bf16 v[30:33], v[158:161], v[170:173], v[30:33]
	v_mfma_f32_16x16x32_bf16 v[42:45], v[150:153], v[174:177], v[42:45]
	v_mfma_f32_16x16x32_bf16 v[46:49], v[158:161], v[174:177], v[46:49]
	v_mfma_f32_16x16x32_bf16 v[50:53], v[150:153], v[186:189], v[50:53]
	v_mfma_f32_16x16x32_bf16 v[54:57], v[158:161], v[186:189], v[54:57]
	v_mfma_f32_16x16x32_bf16 v[58:61], v[150:153], v[190:193], v[58:61]
	v_mfma_f32_16x16x32_bf16 v[62:65], v[158:161], v[190:193], v[62:65]
	s_setprio 0
	s_barrier
	ds_read_b128 v[130:133], v194
	ds_read_b128 v[134:137], v195
	ds_read_b128 v[138:141], v196
	ds_read_b128 v[142:145], v197
	ds_read_b128 v[146:149], v198
	ds_read_b128 v[150:153], v199
	ds_read_b128 v[154:157], v200
	ds_read_b128 v[158:161], v201
	s_add_i32 s20, s20, 0x40000
	s_mov_b32 m0, s39
	ds_read_b128 v[162:165], v248 offset:32768
	ds_read_b128 v[166:169], v248 offset:34816
	ds_read_b128 v[170:173], v249 offset:32768
	ds_read_b128 v[174:177], v249 offset:34816
	ds_read_b128 v[178:181], v248 offset:36864
	ds_read_b128 v[182:185], v248 offset:38912
	ds_read_b128 v[186:189], v249 offset:36864
	ds_read_b128 v[190:193], v249 offset:38912
	buffer_load_dwordx4 v1, s[8:11], s20 offen lds
	s_mov_b32 m0, s41
	s_nop 0
	buffer_load_dwordx4 v234, s[8:11], s20 offen lds
	s_waitcnt vmcnt(8)
	s_waitcnt lgkmcnt(0)
	s_setprio 1
	s_barrier
	v_mfma_f32_16x16x32_bf16 v[74:77], v[130:133], v[162:165], v[74:77]
	v_mfma_f32_16x16x32_bf16 v[70:73], v[138:141], v[162:165], v[70:73]
	v_mfma_f32_16x16x32_bf16 v[66:69], v[130:133], v[166:169], v[66:69]
	v_mfma_f32_16x16x32_bf16 v[82:85], v[138:141], v[166:169], v[82:85]
	v_mfma_f32_16x16x32_bf16 v[78:81], v[130:133], v[178:181], v[78:81]
	v_mfma_f32_16x16x32_bf16 v[90:93], v[138:141], v[178:181], v[90:93]
	v_mfma_f32_16x16x32_bf16 v[86:89], v[130:133], v[182:185], v[86:89]
	v_mfma_f32_16x16x32_bf16 v[102:105], v[138:141], v[182:185], v[102:105]
	v_mfma_f32_16x16x32_bf16 v[74:77], v[134:137], v[170:173], v[74:77]
	v_mfma_f32_16x16x32_bf16 v[70:73], v[142:145], v[170:173], v[70:73]
	v_mfma_f32_16x16x32_bf16 v[66:69], v[134:137], v[174:177], v[66:69]
	v_mfma_f32_16x16x32_bf16 v[82:85], v[142:145], v[174:177], v[82:85]
	v_mfma_f32_16x16x32_bf16 v[78:81], v[134:137], v[186:189], v[78:81]
	v_mfma_f32_16x16x32_bf16 v[90:93], v[142:145], v[186:189], v[90:93]
	v_mfma_f32_16x16x32_bf16 v[86:89], v[134:137], v[190:193], v[86:89]
	v_mfma_f32_16x16x32_bf16 v[102:105], v[142:145], v[190:193], v[102:105]
	v_mfma_f32_16x16x32_bf16 v[98:101], v[146:149], v[162:165], v[98:101]
	v_mfma_f32_16x16x32_bf16 v[94:97], v[154:157], v[162:165], v[94:97]
	v_mfma_f32_16x16x32_bf16 v[106:109], v[146:149], v[166:169], v[106:109]
	v_mfma_f32_16x16x32_bf16 v[110:113], v[154:157], v[166:169], v[110:113]
	v_mfma_f32_16x16x32_bf16 v[114:117], v[146:149], v[178:181], v[114:117]
	v_mfma_f32_16x16x32_bf16 v[118:121], v[154:157], v[178:181], v[118:121]
	v_mfma_f32_16x16x32_bf16 v[122:125], v[146:149], v[182:185], v[122:125]
	v_mfma_f32_16x16x32_bf16 v[126:129], v[154:157], v[182:185], v[126:129]
	v_mfma_f32_16x16x32_bf16 v[98:101], v[150:153], v[170:173], v[98:101]
	v_mfma_f32_16x16x32_bf16 v[94:97], v[158:161], v[170:173], v[94:97]
	v_mfma_f32_16x16x32_bf16 v[106:109], v[150:153], v[174:177], v[106:109]
	v_mfma_f32_16x16x32_bf16 v[110:113], v[158:161], v[174:177], v[110:113]
	v_mfma_f32_16x16x32_bf16 v[114:117], v[150:153], v[186:189], v[114:117]
	v_mfma_f32_16x16x32_bf16 v[118:121], v[158:161], v[186:189], v[118:121]
	v_mfma_f32_16x16x32_bf16 v[122:125], v[150:153], v[190:193], v[122:125]
	v_mfma_f32_16x16x32_bf16 v[126:129], v[158:161], v[190:193], v[126:129]
	s_setprio 0
	s_barrier
	s_mov_b32 m0, s44
	s_add_i32 s20, s19, 0x80
	ds_read_b128 v[162:165], v248 offset:49152
	ds_read_b128 v[166:169], v248 offset:51200
	ds_read_b128 v[170:173], v249 offset:49152
	ds_read_b128 v[174:177], v249 offset:51200
	ds_read_b128 v[178:181], v248 offset:53248
	ds_read_b128 v[182:185], v248 offset:55296
	ds_read_b128 v[186:189], v249 offset:53248
	ds_read_b128 v[190:193], v249 offset:55296
	buffer_load_dwordx4 v233, s[8:11], s20 offen lds
	s_mov_b32 m0, s45
	s_add_i32 s19, s19, 0x40080
	buffer_load_dwordx4 v235, s[8:11], s20 offen lds
	s_mov_b32 m0, s48
	s_nop 0
	buffer_load_dwordx4 v233, s[8:11], s19 offen lds
	s_mov_b32 m0, s49
	s_nop 0
	buffer_load_dwordx4 v235, s[8:11], s19 offen lds
	s_mov_b32 m0, s46
	s_nop 0
	buffer_load_dwordx4 v1, s[8:11], s18 offen lds
	s_mov_b32 m0, s47
	s_nop 0
	buffer_load_dwordx4 v234, s[8:11], s18 offen lds
	s_waitcnt vmcnt(8)
	s_waitcnt lgkmcnt(0)
	s_setprio 1
	s_barrier
	v_mfma_f32_16x16x32_bf16 v[10:13], v[130:133], v[162:165], v[10:13]
	v_mfma_f32_16x16x32_bf16 v[6:9], v[138:141], v[162:165], v[6:9]
	v_mfma_f32_16x16x32_bf16 v[2:5], v[130:133], v[166:169], v[2:5]
	v_mfma_f32_16x16x32_bf16 v[18:21], v[138:141], v[166:169], v[18:21]
	v_mfma_f32_16x16x32_bf16 v[14:17], v[130:133], v[178:181], v[14:17]
	v_mfma_f32_16x16x32_bf16 v[26:29], v[138:141], v[178:181], v[26:29]
	v_mfma_f32_16x16x32_bf16 v[22:25], v[130:133], v[182:185], v[22:25]
	v_mfma_f32_16x16x32_bf16 v[38:41], v[138:141], v[182:185], v[38:41]
	v_mfma_f32_16x16x32_bf16 v[10:13], v[134:137], v[170:173], v[10:13]
	v_mfma_f32_16x16x32_bf16 v[6:9], v[142:145], v[170:173], v[6:9]
	v_mfma_f32_16x16x32_bf16 v[2:5], v[134:137], v[174:177], v[2:5]
	v_mfma_f32_16x16x32_bf16 v[18:21], v[142:145], v[174:177], v[18:21]
	v_mfma_f32_16x16x32_bf16 v[14:17], v[134:137], v[186:189], v[14:17]
	v_mfma_f32_16x16x32_bf16 v[26:29], v[142:145], v[186:189], v[26:29]
	v_mfma_f32_16x16x32_bf16 v[22:25], v[134:137], v[190:193], v[22:25]
	v_mfma_f32_16x16x32_bf16 v[38:41], v[142:145], v[190:193], v[38:41]
	v_mfma_f32_16x16x32_bf16 v[34:37], v[146:149], v[162:165], v[34:37]
	v_mfma_f32_16x16x32_bf16 v[30:33], v[154:157], v[162:165], v[30:33]
	v_mfma_f32_16x16x32_bf16 v[42:45], v[146:149], v[166:169], v[42:45]
	v_mfma_f32_16x16x32_bf16 v[46:49], v[154:157], v[166:169], v[46:49]
	v_mfma_f32_16x16x32_bf16 v[50:53], v[146:149], v[178:181], v[50:53]
	v_mfma_f32_16x16x32_bf16 v[54:57], v[154:157], v[178:181], v[54:57]
	v_mfma_f32_16x16x32_bf16 v[58:61], v[146:149], v[182:185], v[58:61]
	v_mfma_f32_16x16x32_bf16 v[62:65], v[154:157], v[182:185], v[62:65]
	v_mfma_f32_16x16x32_bf16 v[34:37], v[150:153], v[170:173], v[34:37]
	v_mfma_f32_16x16x32_bf16 v[30:33], v[158:161], v[170:173], v[30:33]
	v_mfma_f32_16x16x32_bf16 v[42:45], v[150:153], v[174:177], v[42:45]
	v_mfma_f32_16x16x32_bf16 v[46:49], v[158:161], v[174:177], v[46:49]
	v_mfma_f32_16x16x32_bf16 v[50:53], v[150:153], v[186:189], v[50:53]
	v_mfma_f32_16x16x32_bf16 v[54:57], v[158:161], v[186:189], v[54:57]
	v_mfma_f32_16x16x32_bf16 v[58:61], v[150:153], v[190:193], v[58:61]
	v_mfma_f32_16x16x32_bf16 v[62:65], v[158:161], v[190:193], v[62:65]
	s_setprio 0
	s_barrier
	s_add_i32 s4, s4, 2
	s_addk_i32 s5, 0x100
	s_cmp_gt_u32 s4, 13
	s_cbranch_scc0 .LBB0_841
	s_and_b64 vcc, exec, s[16:17]
	s_cbranch_vccz .LBB0_844
	s_barrier

.LBB0_1122:
	ds_read_b128 v[130:133], v240
	ds_read_b128 v[134:137], v241
	ds_read_b128 v[138:141], v242
	ds_read_b128 v[142:145], v243
	ds_read_b128 v[146:149], v244
	ds_read_b128 v[150:153], v245
	ds_read_b128 v[154:157], v246
	ds_read_b128 v[158:161], v247
	s_add_i32 s8, s31, s53
	s_add_i32 s55, s26, s53
	s_add_i32 s54, s8, 0x800
	s_addk_i32 s55, 0x800
	s_cmp_eq_u32 s53, 0
	s_cselect_b32 s56, s4, s54
	s_cselect_b32 s55, s5, s55
	s_add_i32 s54, s56, 0x80
	s_add_i32 s57, s8, 0x40780
	s_mov_b32 s8, s70
	s_mov_b32 m0, s44
	ds_read_b128 v[162:165], v248
	ds_read_b128 v[166:169], v248 offset:2048
	ds_read_b128 v[170:173], v249
	ds_read_b128 v[174:177], v249 offset:2048
	ds_read_b128 v[178:181], v248 offset:4096
	ds_read_b128 v[182:185], v248 offset:6144
	ds_read_b128 v[186:189], v249 offset:4096
	ds_read_b128 v[190:193], v249 offset:6144
	buffer_load_dwordx4 v1, s[8:11], s57 offen lds
	s_mov_b32 m0, s45
	s_nop 0
	buffer_load_dwordx4 v234, s[8:11], s57 offen lds
	s_waitcnt vmcnt(8)
	s_waitcnt lgkmcnt(0)
	s_setprio 1
	s_barrier
	v_mfma_f32_16x16x32_bf16 v[126:129], v[130:133], v[162:165], v[126:129]
	v_mfma_f32_16x16x32_bf16 v[122:125], v[138:141], v[162:165], v[122:125]
	v_mfma_f32_16x16x32_bf16 v[118:121], v[130:133], v[166:169], v[118:121]
	v_mfma_f32_16x16x32_bf16 v[114:117], v[138:141], v[166:169], v[114:117]
	v_mfma_f32_16x16x32_bf16 v[110:113], v[130:133], v[178:181], v[110:113]
	v_mfma_f32_16x16x32_bf16 v[106:109], v[138:141], v[178:181], v[106:109]
	v_mfma_f32_16x16x32_bf16 v[102:105], v[130:133], v[182:185], v[102:105]
	v_mfma_f32_16x16x32_bf16 v[98:101], v[138:141], v[182:185], v[98:101]
	v_mfma_f32_16x16x32_bf16 v[126:129], v[134:137], v[170:173], v[126:129]
	v_mfma_f32_16x16x32_bf16 v[122:125], v[142:145], v[170:173], v[122:125]
	v_mfma_f32_16x16x32_bf16 v[118:121], v[134:137], v[174:177], v[118:121]
	v_mfma_f32_16x16x32_bf16 v[114:117], v[142:145], v[174:177], v[114:117]
	v_mfma_f32_16x16x32_bf16 v[110:113], v[134:137], v[186:189], v[110:113]
	v_mfma_f32_16x16x32_bf16 v[106:109], v[142:145], v[186:189], v[106:109]
	v_mfma_f32_16x16x32_bf16 v[102:105], v[134:137], v[190:193], v[102:105]
	v_mfma_f32_16x16x32_bf16 v[98:101], v[142:145], v[190:193], v[98:101]
	v_mfma_f32_16x16x32_bf16 v[94:97], v[146:149], v[162:165], v[94:97]
	v_mfma_f32_16x16x32_bf16 v[90:93], v[154:157], v[162:165], v[90:93]
	v_mfma_f32_16x16x32_bf16 v[86:89], v[146:149], v[166:169], v[86:89]
	v_mfma_f32_16x16x32_bf16 v[82:85], v[154:157], v[166:169], v[82:85]
	v_mfma_f32_16x16x32_bf16 v[78:81], v[146:149], v[178:181], v[78:81]
	v_mfma_f32_16x16x32_bf16 v[74:77], v[154:157], v[178:181], v[74:77]
	v_mfma_f32_16x16x32_bf16 v[70:73], v[146:149], v[182:185], v[70:73]
	v_mfma_f32_16x16x32_bf16 v[66:69], v[154:157], v[182:185], v[66:69]
	v_mfma_f32_16x16x32_bf16 v[94:97], v[150:153], v[170:173], v[94:97]
	v_mfma_f32_16x16x32_bf16 v[90:93], v[158:161], v[170:173], v[90:93]
	v_mfma_f32_16x16x32_bf16 v[86:89], v[150:153], v[174:177], v[86:89]
	v_mfma_f32_16x16x32_bf16 v[82:85], v[158:161], v[174:177], v[82:85]
	v_mfma_f32_16x16x32_bf16 v[78:81], v[150:153], v[186:189], v[78:81]
	v_mfma_f32_16x16x32_bf16 v[74:77], v[158:161], v[186:189], v[74:77]
	v_mfma_f32_16x16x32_bf16 v[70:73], v[150:153], v[190:193], v[70:73]
	v_mfma_f32_16x16x32_bf16 v[66:69], v[158:161], v[190:193], v[66:69]
	s_setprio 0
	s_barrier
	s_mov_b32 m0, s23
	ds_read_b128 v[162:165], v248 offset:16384
	ds_read_b128 v[166:169], v248 offset:18432
	ds_read_b128 v[170:173], v249 offset:16384
	ds_read_b128 v[174:177], v249 offset:18432
	ds_read_b128 v[178:181], v248 offset:20480
	ds_read_b128 v[182:185], v248 offset:22528
	ds_read_b128 v[186:189], v249 offset:20480
	ds_read_b128 v[190:193], v249 offset:22528
	buffer_load_dwordx4 v233, s[8:11], s55 offen lds
	s_mov_b32 m0, s24
	s_add_i32 s57, s55, 0x40000
	buffer_load_dwordx4 v235, s[8:11], s55 offen lds
	s_mov_b32 m0, s25
	s_nop 0
	buffer_load_dwordx4 v233, s[8:11], s57 offen lds
	s_mov_b32 m0, s27
	s_nop 0
	buffer_load_dwordx4 v235, s[8:11], s57 offen lds
	s_mov_b32 m0, s22
	s_nop 0
	buffer_load_dwordx4 v1, s[8:11], s56 offen lds
	s_mov_b32 m0, s28
	s_nop 0
	buffer_load_dwordx4 v234, s[8:11], s56 offen lds
	s_waitcnt vmcnt(8)
	s_waitcnt lgkmcnt(0)
	s_setprio 1
	s_barrier
	v_mfma_f32_16x16x32_bf16 v[62:65], v[130:133], v[162:165], v[62:65]
	v_mfma_f32_16x16x32_bf16 v[58:61], v[138:141], v[162:165], v[58:61]
	v_mfma_f32_16x16x32_bf16 v[54:57], v[130:133], v[166:169], v[54:57]
	v_mfma_f32_16x16x32_bf16 v[50:53], v[138:141], v[166:169], v[50:53]
	v_mfma_f32_16x16x32_bf16 v[46:49], v[130:133], v[178:181], v[46:49]
	v_mfma_f32_16x16x32_bf16 v[42:45], v[138:141], v[178:181], v[42:45]
	v_mfma_f32_16x16x32_bf16 v[38:41], v[130:133], v[182:185], v[38:41]
	v_mfma_f32_16x16x32_bf16 v[34:37], v[138:141], v[182:185], v[34:37]
	v_mfma_f32_16x16x32_bf16 v[62:65], v[134:137], v[170:173], v[62:65]
	v_mfma_f32_16x16x32_bf16 v[58:61], v[142:145], v[170:173], v[58:61]
	v_mfma_f32_16x16x32_bf16 v[54:57], v[134:137], v[174:177], v[54:57]
	v_mfma_f32_16x16x32_bf16 v[50:53], v[142:145], v[174:177], v[50:53]
	v_mfma_f32_16x16x32_bf16 v[46:49], v[134:137], v[186:189], v[46:49]
	v_mfma_f32_16x16x32_bf16 v[42:45], v[142:145], v[186:189], v[42:45]
	v_mfma_f32_16x16x32_bf16 v[38:41], v[134:137], v[190:193], v[38:41]
	v_mfma_f32_16x16x32_bf16 v[34:37], v[142:145], v[190:193], v[34:37]
	v_mfma_f32_16x16x32_bf16 v[30:33], v[146:149], v[162:165], v[30:33]
	v_mfma_f32_16x16x32_bf16 v[26:29], v[154:157], v[162:165], v[26:29]
	v_mfma_f32_16x16x32_bf16 v[22:25], v[146:149], v[166:169], v[22:25]
	v_mfma_f32_16x16x32_bf16 v[18:21], v[154:157], v[166:169], v[18:21]
	v_mfma_f32_16x16x32_bf16 v[14:17], v[146:149], v[178:181], v[14:17]
	v_mfma_f32_16x16x32_bf16 v[10:13], v[154:157], v[178:181], v[10:13]
	v_mfma_f32_16x16x32_bf16 v[6:9], v[146:149], v[182:185], v[6:9]
	v_mfma_f32_16x16x32_bf16 v[2:5], v[154:157], v[182:185], v[2:5]
	v_mfma_f32_16x16x32_bf16 v[30:33], v[150:153], v[170:173], v[30:33]
	v_mfma_f32_16x16x32_bf16 v[26:29], v[158:161], v[170:173], v[26:29]
	v_mfma_f32_16x16x32_bf16 v[22:25], v[150:153], v[174:177], v[22:25]
	v_mfma_f32_16x16x32_bf16 v[18:21], v[158:161], v[174:177], v[18:21]
	v_mfma_f32_16x16x32_bf16 v[14:17], v[150:153], v[186:189], v[14:17]
	v_mfma_f32_16x16x32_bf16 v[10:13], v[158:161], v[186:189], v[10:13]
	v_mfma_f32_16x16x32_bf16 v[6:9], v[150:153], v[190:193], v[6:9]
	v_mfma_f32_16x16x32_bf16 v[2:5], v[158:161], v[190:193], v[2:5]
	s_setprio 0
	s_barrier
	ds_read_b128 v[130:133], v194
	ds_read_b128 v[134:137], v195
	ds_read_b128 v[138:141], v196
	ds_read_b128 v[142:145], v197
	ds_read_b128 v[146:149], v198
	ds_read_b128 v[150:153], v199
	ds_read_b128 v[154:157], v200
	ds_read_b128 v[158:161], v201
	s_add_i32 s56, s56, 0x40000
	s_mov_b32 m0, s29
	ds_read_b128 v[162:165], v248 offset:32768
	ds_read_b128 v[166:169], v248 offset:34816
	ds_read_b128 v[170:173], v249 offset:32768
	ds_read_b128 v[174:177], v249 offset:34816
	ds_read_b128 v[178:181], v248 offset:36864
	ds_read_b128 v[182:185], v248 offset:38912
	ds_read_b128 v[186:189], v249 offset:36864
	ds_read_b128 v[190:193], v249 offset:38912
	buffer_load_dwordx4 v1, s[8:11], s56 offen lds
	s_mov_b32 m0, s30
	s_nop 0
	buffer_load_dwordx4 v234, s[8:11], s56 offen lds
	s_waitcnt vmcnt(8)
	s_waitcnt lgkmcnt(0)
	s_setprio 1
	s_barrier
	v_mfma_f32_16x16x32_bf16 v[126:129], v[130:133], v[162:165], v[126:129]
	v_mfma_f32_16x16x32_bf16 v[122:125], v[138:141], v[162:165], v[122:125]
	v_mfma_f32_16x16x32_bf16 v[118:121], v[130:133], v[166:169], v[118:121]
	v_mfma_f32_16x16x32_bf16 v[114:117], v[138:141], v[166:169], v[114:117]
	v_mfma_f32_16x16x32_bf16 v[110:113], v[130:133], v[178:181], v[110:113]
	v_mfma_f32_16x16x32_bf16 v[106:109], v[138:141], v[178:181], v[106:109]
	v_mfma_f32_16x16x32_bf16 v[102:105], v[130:133], v[182:185], v[102:105]
	v_mfma_f32_16x16x32_bf16 v[98:101], v[138:141], v[182:185], v[98:101]
	v_mfma_f32_16x16x32_bf16 v[126:129], v[134:137], v[170:173], v[126:129]
	v_mfma_f32_16x16x32_bf16 v[122:125], v[142:145], v[170:173], v[122:125]
	v_mfma_f32_16x16x32_bf16 v[118:121], v[134:137], v[174:177], v[118:121]
	v_mfma_f32_16x16x32_bf16 v[114:117], v[142:145], v[174:177], v[114:117]
	v_mfma_f32_16x16x32_bf16 v[110:113], v[134:137], v[186:189], v[110:113]
	v_mfma_f32_16x16x32_bf16 v[106:109], v[142:145], v[186:189], v[106:109]
	v_mfma_f32_16x16x32_bf16 v[102:105], v[134:137], v[190:193], v[102:105]
	v_mfma_f32_16x16x32_bf16 v[98:101], v[142:145], v[190:193], v[98:101]
	v_mfma_f32_16x16x32_bf16 v[94:97], v[146:149], v[162:165], v[94:97]
	v_mfma_f32_16x16x32_bf16 v[90:93], v[154:157], v[162:165], v[90:93]
	v_mfma_f32_16x16x32_bf16 v[86:89], v[146:149], v[166:169], v[86:89]
	v_mfma_f32_16x16x32_bf16 v[82:85], v[154:157], v[166:169], v[82:85]
	v_mfma_f32_16x16x32_bf16 v[78:81], v[146:149], v[178:181], v[78:81]
	v_mfma_f32_16x16x32_bf16 v[74:77], v[154:157], v[178:181], v[74:77]
	v_mfma_f32_16x16x32_bf16 v[70:73], v[146:149], v[182:185], v[70:73]
	v_mfma_f32_16x16x32_bf16 v[66:69], v[154:157], v[182:185], v[66:69]
	v_mfma_f32_16x16x32_bf16 v[94:97], v[150:153], v[170:173], v[94:97]
	v_mfma_f32_16x16x32_bf16 v[90:93], v[158:161], v[170:173], v[90:93]
	v_mfma_f32_16x16x32_bf16 v[86:89], v[150:153], v[174:177], v[86:89]
	v_mfma_f32_16x16x32_bf16 v[82:85], v[158:161], v[174:177], v[82:85]
	v_mfma_f32_16x16x32_bf16 v[78:81], v[150:153], v[186:189], v[78:81]
	v_mfma_f32_16x16x32_bf16 v[74:77], v[158:161], v[186:189], v[74:77]
	v_mfma_f32_16x16x32_bf16 v[70:73], v[150:153], v[190:193], v[70:73]
	v_mfma_f32_16x16x32_bf16 v[66:69], v[158:161], v[190:193], v[66:69]
	s_setprio 0
	s_barrier
	s_mov_b32 m0, s35
	s_add_i32 s56, s55, 0x80
	ds_read_b128 v[162:165], v248 offset:49152
	ds_read_b128 v[166:169], v248 offset:51200
	ds_read_b128 v[170:173], v249 offset:49152
	ds_read_b128 v[174:177], v249 offset:51200
	ds_read_b128 v[178:181], v248 offset:53248
	ds_read_b128 v[182:185], v248 offset:55296
	ds_read_b128 v[186:189], v249 offset:53248
	ds_read_b128 v[190:193], v249 offset:55296
	buffer_load_dwordx4 v233, s[8:11], s56 offen lds
	s_mov_b32 m0, s36
	s_add_i32 s55, s55, 0x40080
	buffer_load_dwordx4 v235, s[8:11], s56 offen lds
	s_mov_b32 m0, s39
	s_nop 0
	buffer_load_dwordx4 v233, s[8:11], s55 offen lds
	s_mov_b32 m0, s41
	s_nop 0
	buffer_load_dwordx4 v235, s[8:11], s55 offen lds
	s_mov_b32 m0, s37
	s_nop 0
	buffer_load_dwordx4 v1, s[8:11], s54 offen lds
	s_mov_b32 m0, s38
	s_nop 0
	buffer_load_dwordx4 v234, s[8:11], s54 offen lds
	s_waitcnt vmcnt(8)
	s_waitcnt lgkmcnt(0)
	s_setprio 1
	s_barrier
	v_mfma_f32_16x16x32_bf16 v[62:65], v[130:133], v[162:165], v[62:65]
	v_mfma_f32_16x16x32_bf16 v[58:61], v[138:141], v[162:165], v[58:61]
	v_mfma_f32_16x16x32_bf16 v[54:57], v[130:133], v[166:169], v[54:57]
	v_mfma_f32_16x16x32_bf16 v[50:53], v[138:141], v[166:169], v[50:53]
	v_mfma_f32_16x16x32_bf16 v[46:49], v[130:133], v[178:181], v[46:49]
	v_mfma_f32_16x16x32_bf16 v[42:45], v[138:141], v[178:181], v[42:45]
	v_mfma_f32_16x16x32_bf16 v[38:41], v[130:133], v[182:185], v[38:41]
	v_mfma_f32_16x16x32_bf16 v[34:37], v[138:141], v[182:185], v[34:37]
	v_mfma_f32_16x16x32_bf16 v[62:65], v[134:137], v[170:173], v[62:65]
	v_mfma_f32_16x16x32_bf16 v[58:61], v[142:145], v[170:173], v[58:61]
	v_mfma_f32_16x16x32_bf16 v[54:57], v[134:137], v[174:177], v[54:57]
	v_mfma_f32_16x16x32_bf16 v[50:53], v[142:145], v[174:177], v[50:53]
	v_mfma_f32_16x16x32_bf16 v[46:49], v[134:137], v[186:189], v[46:49]
	v_mfma_f32_16x16x32_bf16 v[42:45], v[142:145], v[186:189], v[42:45]
	v_mfma_f32_16x16x32_bf16 v[38:41], v[134:137], v[190:193], v[38:41]
	v_mfma_f32_16x16x32_bf16 v[34:37], v[142:145], v[190:193], v[34:37]
	v_mfma_f32_16x16x32_bf16 v[30:33], v[146:149], v[162:165], v[30:33]
	v_mfma_f32_16x16x32_bf16 v[26:29], v[154:157], v[162:165], v[26:29]
	v_mfma_f32_16x16x32_bf16 v[22:25], v[146:149], v[166:169], v[22:25]
	v_mfma_f32_16x16x32_bf16 v[18:21], v[154:157], v[166:169], v[18:21]
	v_mfma_f32_16x16x32_bf16 v[14:17], v[146:149], v[178:181], v[14:17]
	v_mfma_f32_16x16x32_bf16 v[10:13], v[154:157], v[178:181], v[10:13]
	v_mfma_f32_16x16x32_bf16 v[6:9], v[146:149], v[182:185], v[6:9]
	v_mfma_f32_16x16x32_bf16 v[2:5], v[154:157], v[182:185], v[2:5]
	v_mfma_f32_16x16x32_bf16 v[30:33], v[150:153], v[170:173], v[30:33]
	v_mfma_f32_16x16x32_bf16 v[26:29], v[158:161], v[170:173], v[26:29]
	v_mfma_f32_16x16x32_bf16 v[22:25], v[150:153], v[174:177], v[22:25]
	v_mfma_f32_16x16x32_bf16 v[18:21], v[158:161], v[174:177], v[18:21]
	v_mfma_f32_16x16x32_bf16 v[14:17], v[150:153], v[186:189], v[14:17]
	v_mfma_f32_16x16x32_bf16 v[10:13], v[158:161], v[186:189], v[10:13]
	v_mfma_f32_16x16x32_bf16 v[6:9], v[150:153], v[190:193], v[6:9]
	v_mfma_f32_16x16x32_bf16 v[2:5], v[158:161], v[190:193], v[2:5]
	s_setprio 0
	s_barrier
	s_add_i32 s33, s33, 2
	s_addk_i32 s53, 0x100
	s_cmp_gt_u32 s33, 13
	s_cbranch_scc0 .LBB0_1122
	s_and_b64 vcc, exec, s[16:17]
	s_cbranch_vccz .LBB0_1125
	s_barrier

.LBB0_1251:
	ds_read_b128 v[130:133], v239
	ds_read_b128 v[134:137], v240
	ds_read_b128 v[138:141], v241
	ds_read_b128 v[142:145], v242
	ds_read_b128 v[146:149], v243
	ds_read_b128 v[150:153], v244
	ds_read_b128 v[154:157], v245
	ds_read_b128 v[158:161], v246
	s_add_i32 s8, s51, s5
	s_add_i32 s31, s46, s5
	s_add_i32 s30, s8, 0x2000
	s_addk_i32 s31, 0x2000
	s_cmp_eq_u32 s5, 0
	s_cselect_b32 s33, s0, s30
	s_cselect_b32 s31, s1, s31
	s_add_i32 s30, s33, 0x80
	s_add_i32 s34, s8, 0x101f80
	s_mov_b32 s8, s70
	s_mov_b32 m0, s61
	ds_read_b128 v[162:165], v247
	ds_read_b128 v[166:169], v247 offset:2048
	ds_read_b128 v[170:173], v248
	ds_read_b128 v[174:177], v248 offset:2048
	ds_read_b128 v[178:181], v247 offset:4096
	ds_read_b128 v[182:185], v247 offset:6144
	ds_read_b128 v[186:189], v248 offset:4096
	ds_read_b128 v[190:193], v248 offset:6144
	buffer_load_dwordx4 v230, s[8:11], s34 offen lds
	s_mov_b32 m0, s64
	s_nop 0
	buffer_load_dwordx4 v233, s[8:11], s34 offen lds
	s_waitcnt vmcnt(8)
	s_waitcnt lgkmcnt(0)
	s_setprio 1
	s_barrier
	v_mfma_f32_16x16x32_bf16 v[74:77], v[130:133], v[162:165], v[74:77]
	v_mfma_f32_16x16x32_bf16 v[70:73], v[138:141], v[162:165], v[70:73]
	v_mfma_f32_16x16x32_bf16 v[66:69], v[130:133], v[166:169], v[66:69]
	v_mfma_f32_16x16x32_bf16 v[82:85], v[138:141], v[166:169], v[82:85]
	v_mfma_f32_16x16x32_bf16 v[78:81], v[130:133], v[178:181], v[78:81]
	v_mfma_f32_16x16x32_bf16 v[90:93], v[138:141], v[178:181], v[90:93]
	v_mfma_f32_16x16x32_bf16 v[86:89], v[130:133], v[182:185], v[86:89]
	v_mfma_f32_16x16x32_bf16 v[102:105], v[138:141], v[182:185], v[102:105]
	v_mfma_f32_16x16x32_bf16 v[74:77], v[134:137], v[170:173], v[74:77]
	v_mfma_f32_16x16x32_bf16 v[70:73], v[142:145], v[170:173], v[70:73]
	v_mfma_f32_16x16x32_bf16 v[66:69], v[134:137], v[174:177], v[66:69]
	v_mfma_f32_16x16x32_bf16 v[82:85], v[142:145], v[174:177], v[82:85]
	v_mfma_f32_16x16x32_bf16 v[78:81], v[134:137], v[186:189], v[78:81]
	v_mfma_f32_16x16x32_bf16 v[90:93], v[142:145], v[186:189], v[90:93]
	v_mfma_f32_16x16x32_bf16 v[86:89], v[134:137], v[190:193], v[86:89]
	v_mfma_f32_16x16x32_bf16 v[102:105], v[142:145], v[190:193], v[102:105]
	v_mfma_f32_16x16x32_bf16 v[98:101], v[146:149], v[162:165], v[98:101]
	v_mfma_f32_16x16x32_bf16 v[94:97], v[154:157], v[162:165], v[94:97]
	v_mfma_f32_16x16x32_bf16 v[106:109], v[146:149], v[166:169], v[106:109]
	v_mfma_f32_16x16x32_bf16 v[110:113], v[154:157], v[166:169], v[110:113]
	v_mfma_f32_16x16x32_bf16 v[114:117], v[146:149], v[178:181], v[114:117]
	v_mfma_f32_16x16x32_bf16 v[118:121], v[154:157], v[178:181], v[118:121]
	v_mfma_f32_16x16x32_bf16 v[122:125], v[146:149], v[182:185], v[122:125]
	v_mfma_f32_16x16x32_bf16 v[126:129], v[154:157], v[182:185], v[126:129]
	v_mfma_f32_16x16x32_bf16 v[98:101], v[150:153], v[170:173], v[98:101]
	v_mfma_f32_16x16x32_bf16 v[94:97], v[158:161], v[170:173], v[94:97]
	v_mfma_f32_16x16x32_bf16 v[106:109], v[150:153], v[174:177], v[106:109]
	v_mfma_f32_16x16x32_bf16 v[110:113], v[158:161], v[174:177], v[110:113]
	v_mfma_f32_16x16x32_bf16 v[114:117], v[150:153], v[186:189], v[114:117]
	v_mfma_f32_16x16x32_bf16 v[118:121], v[158:161], v[186:189], v[118:121]
	v_mfma_f32_16x16x32_bf16 v[122:125], v[150:153], v[190:193], v[122:125]
	v_mfma_f32_16x16x32_bf16 v[126:129], v[158:161], v[190:193], v[126:129]
	s_setprio 0
	s_barrier
	s_mov_b32 m0, s43
	ds_read_b128 v[162:165], v247 offset:16384
	ds_read_b128 v[166:169], v247 offset:18432
	ds_read_b128 v[170:173], v248 offset:16384
	ds_read_b128 v[174:177], v248 offset:18432
	ds_read_b128 v[178:181], v247 offset:20480
	ds_read_b128 v[182:185], v247 offset:22528
	ds_read_b128 v[186:189], v248 offset:20480
	ds_read_b128 v[190:193], v248 offset:22528
	buffer_load_dwordx4 v231, s[8:11], s31 offen lds
	s_mov_b32 m0, s44
	s_add_i32 s34, s31, 0x100000
	buffer_load_dwordx4 v234, s[8:11], s31 offen lds
	s_mov_b32 m0, s45
	s_nop 0
	buffer_load_dwordx4 v231, s[8:11], s34 offen lds
	s_mov_b32 m0, s47
	s_nop 0
	buffer_load_dwordx4 v234, s[8:11], s34 offen lds
	s_mov_b32 m0, s42
	s_nop 0
	buffer_load_dwordx4 v230, s[8:11], s33 offen lds
	s_mov_b32 m0, s48
	s_nop 0
	buffer_load_dwordx4 v233, s[8:11], s33 offen lds
	s_waitcnt vmcnt(8)
	s_waitcnt lgkmcnt(0)
	s_setprio 1
	s_barrier
	v_mfma_f32_16x16x32_bf16 v[10:13], v[130:133], v[162:165], v[10:13]
	v_mfma_f32_16x16x32_bf16 v[6:9], v[138:141], v[162:165], v[6:9]
	v_mfma_f32_16x16x32_bf16 v[0:3], v[130:133], v[166:169], v[2:5]
	v_mfma_f32_16x16x32_bf16 v[18:21], v[138:141], v[166:169], v[18:21]
	v_mfma_f32_16x16x32_bf16 v[14:17], v[130:133], v[178:181], v[14:17]
	v_mfma_f32_16x16x32_bf16 v[26:29], v[138:141], v[178:181], v[26:29]
	v_mfma_f32_16x16x32_bf16 v[22:25], v[130:133], v[182:185], v[22:25]
	v_mfma_f32_16x16x32_bf16 v[38:41], v[138:141], v[182:185], v[38:41]
	v_mfma_f32_16x16x32_bf16 v[10:13], v[134:137], v[170:173], v[10:13]
	v_mfma_f32_16x16x32_bf16 v[6:9], v[142:145], v[170:173], v[6:9]
	v_mfma_f32_16x16x32_bf16 v[0:3], v[134:137], v[174:177], v[0:3]
	v_mfma_f32_16x16x32_bf16 v[18:21], v[142:145], v[174:177], v[18:21]
	v_mfma_f32_16x16x32_bf16 v[14:17], v[134:137], v[186:189], v[14:17]
	v_mfma_f32_16x16x32_bf16 v[26:29], v[142:145], v[186:189], v[26:29]
	v_mfma_f32_16x16x32_bf16 v[22:25], v[134:137], v[190:193], v[22:25]
	v_mfma_f32_16x16x32_bf16 v[38:41], v[142:145], v[190:193], v[38:41]
	v_mfma_f32_16x16x32_bf16 v[34:37], v[146:149], v[162:165], v[34:37]
	v_mfma_f32_16x16x32_bf16 v[30:33], v[154:157], v[162:165], v[30:33]
	v_mfma_f32_16x16x32_bf16 v[42:45], v[146:149], v[166:169], v[42:45]
	v_mfma_f32_16x16x32_bf16 v[46:49], v[154:157], v[166:169], v[46:49]
	v_mfma_f32_16x16x32_bf16 v[50:53], v[146:149], v[178:181], v[50:53]
	v_mfma_f32_16x16x32_bf16 v[54:57], v[154:157], v[178:181], v[54:57]
	v_mfma_f32_16x16x32_bf16 v[58:61], v[146:149], v[182:185], v[58:61]
	v_mfma_f32_16x16x32_bf16 v[62:65], v[154:157], v[182:185], v[62:65]
	v_mfma_f32_16x16x32_bf16 v[34:37], v[150:153], v[170:173], v[34:37]
	v_mfma_f32_16x16x32_bf16 v[30:33], v[158:161], v[170:173], v[30:33]
	v_mfma_f32_16x16x32_bf16 v[42:45], v[150:153], v[174:177], v[42:45]
	v_mfma_f32_16x16x32_bf16 v[46:49], v[158:161], v[174:177], v[46:49]
	v_mfma_f32_16x16x32_bf16 v[50:53], v[150:153], v[186:189], v[50:53]
	v_mfma_f32_16x16x32_bf16 v[54:57], v[158:161], v[186:189], v[54:57]
	v_mfma_f32_16x16x32_bf16 v[58:61], v[150:153], v[190:193], v[58:61]
	v_mfma_f32_16x16x32_bf16 v[62:65], v[158:161], v[190:193], v[62:65]
	s_setprio 0
	s_barrier
	ds_read_b128 v[130:133], v194
	ds_read_b128 v[134:137], v195
	ds_read_b128 v[138:141], v196
	ds_read_b128 v[142:145], v197
	ds_read_b128 v[146:149], v198
	ds_read_b128 v[150:153], v199
	ds_read_b128 v[154:157], v200
	ds_read_b128 v[158:161], v201
	s_add_i32 s33, s33, 0x100000
	s_mov_b32 m0, s49
	ds_read_b128 v[162:165], v247 offset:32768
	ds_read_b128 v[166:169], v247 offset:34816
	ds_read_b128 v[170:173], v248 offset:32768
	ds_read_b128 v[174:177], v248 offset:34816
	ds_read_b128 v[178:181], v247 offset:36864
	ds_read_b128 v[182:185], v247 offset:38912
	ds_read_b128 v[186:189], v248 offset:36864
	ds_read_b128 v[190:193], v248 offset:38912
	buffer_load_dwordx4 v230, s[8:11], s33 offen lds
	s_mov_b32 m0, s50
	s_nop 0
	buffer_load_dwordx4 v233, s[8:11], s33 offen lds
	s_waitcnt vmcnt(8)
	s_waitcnt lgkmcnt(0)
	s_setprio 1
	s_barrier
	v_mfma_f32_16x16x32_bf16 v[74:77], v[130:133], v[162:165], v[74:77]
	v_mfma_f32_16x16x32_bf16 v[70:73], v[138:141], v[162:165], v[70:73]
	v_mfma_f32_16x16x32_bf16 v[66:69], v[130:133], v[166:169], v[66:69]
	v_mfma_f32_16x16x32_bf16 v[82:85], v[138:141], v[166:169], v[82:85]
	v_mfma_f32_16x16x32_bf16 v[78:81], v[130:133], v[178:181], v[78:81]
	v_mfma_f32_16x16x32_bf16 v[90:93], v[138:141], v[178:181], v[90:93]
	v_mfma_f32_16x16x32_bf16 v[86:89], v[130:133], v[182:185], v[86:89]
	v_mfma_f32_16x16x32_bf16 v[102:105], v[138:141], v[182:185], v[102:105]
	v_mfma_f32_16x16x32_bf16 v[74:77], v[134:137], v[170:173], v[74:77]
	v_mfma_f32_16x16x32_bf16 v[70:73], v[142:145], v[170:173], v[70:73]
	v_mfma_f32_16x16x32_bf16 v[66:69], v[134:137], v[174:177], v[66:69]
	v_mfma_f32_16x16x32_bf16 v[82:85], v[142:145], v[174:177], v[82:85]
	v_mfma_f32_16x16x32_bf16 v[78:81], v[134:137], v[186:189], v[78:81]
	v_mfma_f32_16x16x32_bf16 v[90:93], v[142:145], v[186:189], v[90:93]
	v_mfma_f32_16x16x32_bf16 v[86:89], v[134:137], v[190:193], v[86:89]
	v_mfma_f32_16x16x32_bf16 v[102:105], v[142:145], v[190:193], v[102:105]
	v_mfma_f32_16x16x32_bf16 v[98:101], v[146:149], v[162:165], v[98:101]
	v_mfma_f32_16x16x32_bf16 v[94:97], v[154:157], v[162:165], v[94:97]
	v_mfma_f32_16x16x32_bf16 v[106:109], v[146:149], v[166:169], v[106:109]
	v_mfma_f32_16x16x32_bf16 v[110:113], v[154:157], v[166:169], v[110:113]
	v_mfma_f32_16x16x32_bf16 v[114:117], v[146:149], v[178:181], v[114:117]
	v_mfma_f32_16x16x32_bf16 v[118:121], v[154:157], v[178:181], v[118:121]
	v_mfma_f32_16x16x32_bf16 v[122:125], v[146:149], v[182:185], v[122:125]
	v_mfma_f32_16x16x32_bf16 v[126:129], v[154:157], v[182:185], v[126:129]
	v_mfma_f32_16x16x32_bf16 v[98:101], v[150:153], v[170:173], v[98:101]
	v_mfma_f32_16x16x32_bf16 v[94:97], v[158:161], v[170:173], v[94:97]
	v_mfma_f32_16x16x32_bf16 v[106:109], v[150:153], v[174:177], v[106:109]
	v_mfma_f32_16x16x32_bf16 v[110:113], v[158:161], v[174:177], v[110:113]
	v_mfma_f32_16x16x32_bf16 v[114:117], v[150:153], v[186:189], v[114:117]
	v_mfma_f32_16x16x32_bf16 v[118:121], v[158:161], v[186:189], v[118:121]
	v_mfma_f32_16x16x32_bf16 v[122:125], v[150:153], v[190:193], v[122:125]
	v_mfma_f32_16x16x32_bf16 v[126:129], v[158:161], v[190:193], v[126:129]
	s_setprio 0
	s_barrier
	s_mov_b32 m0, s53
	s_add_i32 s33, s31, 0x80
	ds_read_b128 v[162:165], v247 offset:49152
	ds_read_b128 v[166:169], v247 offset:51200
	ds_read_b128 v[170:173], v248 offset:49152
	ds_read_b128 v[174:177], v248 offset:51200
	ds_read_b128 v[178:181], v247 offset:53248
	ds_read_b128 v[182:185], v247 offset:55296
	ds_read_b128 v[186:189], v248 offset:53248
	ds_read_b128 v[190:193], v248 offset:55296
	buffer_load_dwordx4 v231, s[8:11], s33 offen lds
	s_mov_b32 m0, s54
	s_add_i32 s31, s31, 0x100080
	buffer_load_dwordx4 v234, s[8:11], s33 offen lds
	s_mov_b32 m0, s57
	s_nop 0
	buffer_load_dwordx4 v231, s[8:11], s31 offen lds
	s_mov_b32 m0, s58
	s_nop 0
	buffer_load_dwordx4 v234, s[8:11], s31 offen lds
	s_mov_b32 m0, s55
	s_nop 0
	buffer_load_dwordx4 v230, s[8:11], s30 offen lds
	s_mov_b32 m0, s56
	s_nop 0
	buffer_load_dwordx4 v233, s[8:11], s30 offen lds
	s_waitcnt vmcnt(8)
	s_waitcnt lgkmcnt(0)
	s_setprio 1
	s_barrier
	v_mfma_f32_16x16x32_bf16 v[10:13], v[130:133], v[162:165], v[10:13]
	v_mfma_f32_16x16x32_bf16 v[4:7], v[138:141], v[162:165], v[6:9]
	v_mfma_f32_16x16x32_bf16 v[0:3], v[130:133], v[166:169], v[0:3]
	v_mfma_f32_16x16x32_bf16 v[18:21], v[138:141], v[166:169], v[18:21]
	v_mfma_f32_16x16x32_bf16 v[14:17], v[130:133], v[178:181], v[14:17]
	v_mfma_f32_16x16x32_bf16 v[26:29], v[138:141], v[178:181], v[26:29]
	v_mfma_f32_16x16x32_bf16 v[22:25], v[130:133], v[182:185], v[22:25]
	v_mfma_f32_16x16x32_bf16 v[38:41], v[138:141], v[182:185], v[38:41]
	v_mfma_f32_16x16x32_bf16 v[10:13], v[134:137], v[170:173], v[10:13]
	v_mfma_f32_16x16x32_bf16 v[6:9], v[142:145], v[170:173], v[4:7]
	v_mfma_f32_16x16x32_bf16 v[2:5], v[134:137], v[174:177], v[0:3]
	v_mfma_f32_16x16x32_bf16 v[18:21], v[142:145], v[174:177], v[18:21]
	v_mfma_f32_16x16x32_bf16 v[14:17], v[134:137], v[186:189], v[14:17]
	v_mfma_f32_16x16x32_bf16 v[26:29], v[142:145], v[186:189], v[26:29]
	v_mfma_f32_16x16x32_bf16 v[22:25], v[134:137], v[190:193], v[22:25]
	v_mfma_f32_16x16x32_bf16 v[38:41], v[142:145], v[190:193], v[38:41]
	v_mfma_f32_16x16x32_bf16 v[34:37], v[146:149], v[162:165], v[34:37]
	v_mfma_f32_16x16x32_bf16 v[30:33], v[154:157], v[162:165], v[30:33]
	v_mfma_f32_16x16x32_bf16 v[42:45], v[146:149], v[166:169], v[42:45]
	v_mfma_f32_16x16x32_bf16 v[46:49], v[154:157], v[166:169], v[46:49]
	v_mfma_f32_16x16x32_bf16 v[50:53], v[146:149], v[178:181], v[50:53]
	v_mfma_f32_16x16x32_bf16 v[54:57], v[154:157], v[178:181], v[54:57]
	v_mfma_f32_16x16x32_bf16 v[58:61], v[146:149], v[182:185], v[58:61]
	v_mfma_f32_16x16x32_bf16 v[62:65], v[154:157], v[182:185], v[62:65]
	v_mfma_f32_16x16x32_bf16 v[34:37], v[150:153], v[170:173], v[34:37]
	v_mfma_f32_16x16x32_bf16 v[30:33], v[158:161], v[170:173], v[30:33]
	v_mfma_f32_16x16x32_bf16 v[42:45], v[150:153], v[174:177], v[42:45]
	v_mfma_f32_16x16x32_bf16 v[46:49], v[158:161], v[174:177], v[46:49]
	v_mfma_f32_16x16x32_bf16 v[50:53], v[150:153], v[186:189], v[50:53]
	v_mfma_f32_16x16x32_bf16 v[54:57], v[158:161], v[186:189], v[54:57]
	v_mfma_f32_16x16x32_bf16 v[58:61], v[150:153], v[190:193], v[58:61]
	v_mfma_f32_16x16x32_bf16 v[62:65], v[158:161], v[190:193], v[62:65]
	s_setprio 0
	s_barrier
	s_add_i32 s4, s4, 2
	s_addk_i32 s5, 0x100
	s_cmp_gt_u32 s4, 61
	s_cbranch_scc0 .LBB0_1251
	s_and_b64 vcc, exec, s[18:19]
	s_cbranch_vccz .LBB0_1254
	s_barrier
